# GEMM in-proj tile order: each XCD works a 4x4 tile block per round (was 8x2) for fewer unique A/B slabs per L2
# speedup vs baseline: 1.0193x; 1.0088x over previous
.LBB0_177:
	v_writelane_b32 v254, s30, 44
	v_mov_b32_e32 v12, v247
	s_nop 0
	v_writelane_b32 v254, s31, 45
	v_writelane_b32 v254, s20, 46
	v_writelane_b32 v254, s13, 47
	v_writelane_b32 v254, s54, 48
	v_writelane_b32 v254, s88, 49
	s_load_dwordx4 s[8:11], s[88:89], 0x78
	s_nop 0
	v_writelane_b32 v254, s89, 50
	s_lshl_b32 s88, s49, 3
	s_waitcnt lgkmcnt(0)
	v_writelane_b32 v254, s8, 51
	s_add_i32 s12, s88, 0xffff
	s_nop 0
	v_writelane_b32 v254, s9, 52
	v_writelane_b32 v254, s10, 53
	v_writelane_b32 v254, s11, 54
	v_readlane_b32 s9, v253, 9
	s_mul_i32 s9, s9, s49
	v_readlane_b32 s10, v253, 7
	s_lshr_b32 s11, s10, 2
	s_lshl_b32 s11, s11, 3
	s_and_b32 s13, s10, 3
	s_or_b32 s11, s11, s13
	s_cmp_ge_u32 s49, 16
	s_cselect_b32 s10, s11, s10
	s_or_b32 s9, s9, s10
	s_ff1_i32_b32 s10, s88
	s_lshr_b32 s10, s9, s10
	s_lshl_b32 s10, s10, 3
	s_sub_i32 s11, 16, s10
	s_min_i32 s11, s11, 8
	s_sext_i32_i16 s13, s11
	v_cvt_f32_i32_e32 v0, s13
	s_and_b32 s12, s9, s12
	s_sext_i32_i16 s9, s12
	v_cvt_f32_i32_e32 v1, s9
	v_rcp_iflag_f32_e32 v2, v0
	s_xor_b32 s9, s9, s13
	s_ashr_i32 s9, s9, 30
	s_or_b32 s9, s9, 1
	v_mul_f32_e32 v2, v1, v2
	v_trunc_f32_e32 v2, v2
	v_fma_f32 v1, -v2, v0, v1
	v_cvt_i32_f32_e32 v2, v2
	v_cmp_ge_f32_e64 s[20:21], |v1|, |v0|
	s_and_b64 s[20:21], s[20:21], exec
	s_cselect_b32 s9, s9, 0
	v_readfirstlane_b32 s13, v2
	s_add_i32 s13, s13, s9
	v_readfirstlane_b32 s8, v12
	s_sext_i32_i16 s46, s13
	s_and_b64 vcc, exec, s[2:3]
	s_cbranch_vccnz .LBB0_179
	v_cvt_f32_i32_e32 v0, s82
	v_cvt_f32_i32_e32 v1, s46
	s_xor_b32 s6, s46, s82
	s_ashr_i32 s6, s6, 30
	v_rcp_iflag_f32_e32 v2, v0
	s_or_b32 s9, s6, 1
	v_mul_f32_e32 v2, v1, v2
	v_trunc_f32_e32 v2, v2
	v_fma_f32 v1, -v2, v0, v1
	v_cvt_i32_f32_e32 v2, v2
	v_cmp_ge_f32_e64 s[6:7], |v1|, |v0|
	s_and_b64 s[6:7], s[6:7], exec
	s_cselect_b32 s6, s9, 0
	v_readfirstlane_b32 s7, v2
	s_add_i32 s6, s7, s6
	s_bfe_i64 s[6:7], s[6:7], 0x100000
	s_mul_i32 s7, s28, s7
	s_mul_hi_u32 s9, s28, s6
	s_add_i32 s7, s9, s7
	s_mul_i32 s6, s28, s6
	s_lshl_b64 s[6:7], s[6:7], 1

.LBB0_182:
	s_add_i32 s70, s87, 1
	s_ashr_i32 s71, s70, 31
	s_lshl_b64 s[2:3], s[70:71], 7
	s_or_b64 s[2:3], s[2:3], s[72:73]
	v_cmp_ge_i64_e64 s[4:5], s[2:3], v[222:223]
	s_mov_b64 s[62:63], s[72:73]
	v_cmp_lt_i64_e64 s[8:9], s[2:3], v[222:223]
	s_and_b64 vcc, exec, s[4:5]
	s_cbranch_vccnz .LBB0_184
	s_ashr_i32 s3, s2, 31
	s_lshr_b32 s3, s3, 29
	s_add_i32 s3, s2, s3
	s_ashr_i32 s6, s3, 3
	s_lshr_b32 s7, s6, 2
	s_and_b32 s7, s7, 7
	s_lshl_b32 s10, s7, 1
	s_and_b32 s10, s10, 6
	s_lshr_b32 s7, s7, 2
	s_or_b32 s7, s7, s10
	s_lshl_b32 s7, s7, 2
	s_andn2_b32 s10, s6, 0x1c
	s_or_b32 s7, s7, s10
	s_cmp_ge_u32 s49, 16
	s_cselect_b32 s6, s7, s6
	s_and_b32 s3, s3, -8
	s_sub_i32 s2, s2, s3
	s_waitcnt vmcnt(0)
	v_mov_b32_e32 v128, s2
	v_alignbit_b32 v128, s49, v128, 31
	v_readlane_b32 s7, v255, 1
	v_readfirstlane_b32 s3, v128
	s_mul_i32 s2, s3, s2
	s_add_i32 s2, s2, s6
	s_abs_i32 s6, s2
	s_mul_hi_u32 s7, s6, s7
	s_mul_i32 s10, s7, s88
	s_sub_i32 s6, s6, s10
	s_ashr_i32 s3, s2, 31
	s_add_i32 s10, s7, 1
	s_sub_i32 s11, s6, s88
	s_cmp_ge_u32 s6, s88
	s_cselect_b32 s7, s10, s7
	s_cselect_b32 s6, s11, s6
	s_add_i32 s10, s7, 1
	s_cmp_ge_u32 s6, s88
	s_cselect_b32 s6, s10, s7
	s_xor_b32 s6, s6, s3
	s_sub_i32 s3, s6, s3
	s_lshl_b32 s6, s3, 3
	s_sub_i32 s7, 16, s6
	s_min_i32 s7, s7, 8
	s_abs_i32 s10, s7
	v_cvt_f32_u32_e32 v128, s10
	s_sub_i32 s12, 0, s10
	s_mul_i32 s3, s3, s88
	s_sub_i32 s2, s2, s3
	v_rcp_iflag_f32_e32 v128, v128
	s_abs_i32 s11, s2
	s_xor_b32 s3, s2, s7
	s_ashr_i32 s3, s3, 31
	v_mul_f32_e32 v128, 0x4f7ffffe, v128
	v_cvt_u32_f32_e32 v128, v128
	s_nop 0
	v_readfirstlane_b32 s13, v128
	s_mul_i32 s12, s12, s13
	s_mul_hi_u32 s12, s13, s12
	s_add_i32 s13, s13, s12
	s_mul_hi_u32 s12, s11, s13
	s_mul_i32 s13, s12, s10
	s_sub_i32 s11, s11, s13
	s_add_i32 s13, s12, 1
	s_sub_i32 s24, s11, s10
	s_cmp_ge_u32 s11, s10
	s_cselect_b32 s12, s13, s12
	s_cselect_b32 s11, s24, s11
	s_add_i32 s13, s12, 1
	s_cmp_ge_u32 s11, s10
	s_cselect_b32 s10, s13, s12
	s_xor_b32 s10, s10, s3
	s_sub_i32 s33, s10, s3
	s_mul_i32 s3, s33, s7
	s_sub_i32 s2, s2, s3
	s_add_i32 s3, s6, s60
	s_add_i32 s50, s3, s2
	s_lshl_b32 s2, s70, 3
	s_add_i32 s33, s33, s2
	s_add_i32 s3, s49, -1
	s_and_b32 s33, s33, s3
